# Down phase: odd workgroups (odd XCDs) run the meta-row GEMM after the main GEMM instead of before, to stagger the residual-epilogue HBM bursts between XCD halves
# baseline (speedup 1.0000x reference)
; #define LAS __attribute__((address_space(3)))
; template <int MODE>
; __device__ __forceinline__ void meta_gemm(LAS unsigned char* lds, const bf16* A  , int lda, int kst  , const bf16* Bt, int K, int ncc, const MetaEpi& e, int G, int c) {
;     constexpr int NB = MODE == 0 ? 2 : 1, NP = 1 + NB, PSTR = 144, PANEL = 32 * PSTR, WREG = 14336;
;     static_assert(NP * PANEL <= WREG && NB * 4096 <= WREG && 8 * WREG <= 131072, "meta LDS");
;     int tid_ = threadIdx.x; asm volatile("" : "+v"(tid_));
;     const int tid = tid_, lane = tid & 63, wave = __builtin_amdgcn_readfirstlane(tid >> 6), l32 = lane & 31, hh = lane >> 5;
;     const int nst = K / 64, s0 = (nst * wave) >> 3, s1 = (nst * (wave + 1)) >> 3;
;     LAS unsigned char* wl = lds + wave * WREG;
;     const int lrow = lane >> 3, lch = lane & 7;
;     const int dup = e.dup, nitems = dup ? ncc : 8 * ncc;
; #pragma unroll 1
;     for (int item = c; item < nitems; item += G) {
;         const int rb = dup ? 0 : (item & 7), cc = dup ? item : (item >> 3);
;         const bf16* ag = A + (size_t)(32 * rb + lrow) * lda + lch * 8;
; __global__ void __launch_bounds__(512, 2) fwd_megakernel(Args a) {
;     ...
;             if (f < 3) { const MetaEpi me{nullptr, nullptr, 0, f == 0 ? a.meta : nullptr, hb, ssq + (size_t)(np + 1) * M, 0.5f, f == 0 ? 1 : 0};
;                 meta_gemm<2>(lds, act + (size_t)128 * (FF / 64) * 16384, 64, 16384, (const bf16*)(ws + WS_WDN) + (size_t)f * D * FF, FF, D / 32, me, G, c); }
.LBB0_187:
	s_mov_b32 s98, 0
	s_or_b64 exec, exec, s[0:1]
	s_mov_b64 s[10:11], -1
	s_and_b64 vcc, exec, s[44:45]
	s_waitcnt lgkmcnt(0)
	s_barrier
	s_cbranch_vccz .LBB0_205
.Ldm_meta_entry:
	v_readlane_b32 s0, v255, 28
	s_add_i32 s58, s0, 1
	s_cmp_eq_u32 s56, 0
	s_cselect_b64 s[10:11], -1, 0
	s_and_b64 s[6:7], s[10:11], exec
	v_mov_b32_e32 v0, v192
	s_cselect_b32 s6, 32, 0x100
	s_mul_hi_i32 s1, s58, 0x40800
	s_mul_i32 s0, s58, 0x40800
	s_cmp_eq_u32 s98, 2
	s_cbranch_scc1 .Ldm_norm
	s_bitcmp1_b32 s2, 0
	s_cbranch_scc0 .Ldm_norm
	s_cmp_ge_i32 s2, s6
	s_cbranch_scc1 .Ldm_norm
	s_mov_b32 s98, 1
	v_readfirstlane_b32 s14, v0
	s_branch .LBB0_204
.Ldm_norm:
	s_cmp_ge_i32 s2, s6
	v_readfirstlane_b32 s14, v0
	s_cbranch_scc1 .LBB0_204
	s_ashr_i32 s15, s14, 6
	s_mul_i32 s7, s15, 44
	s_ashr_i32 s20, s7, 3
	s_add_i32 s7, s7, 44
	s_ashr_i32 s7, s7, 3
	s_mul_i32 s17, s56, 0x580000
	v_readlane_b32 s4, v254, 9
	s_mul_hi_u32 s16, s56, 0x580000
	s_add_u32 s24, s4, s17
	v_readlane_b32 s4, v254, 10
	s_addc_u32 s25, s4, s16
	s_mul_i32 s16, s15, 0x3800
	s_add_i32 s16, s16, 0
	v_lshlrev_b32_e32 v4, 4, v0
	v_readlane_b32 s4, v254, 11
	s_add_i32 s17, s7, -1
	v_and_b32_e32 v194, 0x70, v4
	v_readlane_b32 s5, v254, 12
	s_cmp_lt_i32 s20, s7
	v_and_b32_e32 v3, 31, v0
	v_lshl_add_u64 v[16:17], s[4:5], 0, v[194:195]
	v_lshl_add_u64 v[18:19], s[24:25], 0, v[194:195]
	s_cselect_b64 s[24:25], -1, 0
	v_mov_b32_e32 v5, s16
	s_movk_i32 s4, 0x90
	s_ashr_i32 s14, s14, 4
	v_bfe_u32 v2, v0, 5, 1
	v_mad_u32_u24 v5, v3, s4, v5
	s_and_b32 s14, s14, -8
	v_readlane_b32 s4, v254, 13
	v_lshlrev_b32_e32 v6, 4, v2
	s_lshl_b32 s21, s15, 1
	v_lshl_or_b32 v2, v2, 2, s14
	s_lshl_b32 s14, s15, 9
	v_readlane_b32 s5, v254, 14
	v_and_or_b32 v32, s21, 2, v2
	s_add_i32 s26, s14, 0
	s_and_b64 s[14:15], s[10:11], s[4:5]
	s_ashr_i32 s21, s20, 31
	s_add_i32 s27, s26, 0x11800
	s_add_i32 s28, s26, 0x11900
	s_add_i32 s29, s26, 0x15000
	s_add_i32 s30, s26, 0x15100
	s_add_i32 s31, s26, 0x18800
	s_add_i32 s34, s26, 0x18900
	s_xor_b64 s[38:39], s[14:15], -1
	s_lshl_b32 s35, s20, 6
	s_lshl_b64 s[14:15], s[20:21], 15
	v_readlane_b32 s4, v255, 8
	v_and_b32_e32 v1, 63, v0
	v_bfe_u32 v30, v0, 3, 3
	v_lshlrev_b32_e32 v0, 12, v0
	v_readlane_b32 s72, v253, 3
	s_add_u32 s14, s4, s14
	v_readlane_b32 s4, v255, 9
	v_lshlrev_b32_e32 v31, 2, v1
	v_cmp_gt_u32_e64 s[36:37], 32, v1
	v_and_b32_e32 v0, 0xf000, v0
	v_mov_b32_e32 v1, v195
	v_readlane_b32 s73, v253, 4
	v_readlane_b32 s74, v253, 5
	v_readlane_b32 s75, v253, 6
	v_readlane_b32 s76, v253, 7
	v_readlane_b32 s77, v253, 8
	v_readlane_b32 s78, v253, 9
	v_readlane_b32 s79, v253, 10
	v_readlane_b32 s80, v253, 11
	v_readlane_b32 s81, v253, 12
	v_readlane_b32 s82, v253, 13
	v_readlane_b32 s83, v253, 14
	v_readlane_b32 s84, v253, 15
	v_readlane_b32 s85, v253, 16
	v_readlane_b32 s86, v253, 17
	v_readlane_b32 s87, v253, 18
	s_addc_u32 s15, s4, s15
	v_readlane_b32 s4, v253, 0
	v_add_u32_e32 v4, s16, v194
	v_mul_u32_u24_e32 v2, 0x90, v30
	v_lshlrev_b32_e32 v7, 6, v30
	v_lshl_add_u64 v[20:21], s[74:75], 0, v[0:1]
	v_readlane_b32 s72, v255, 12
	s_add_u32 s40, s4, s0
	v_readlane_b32 s4, v253, 1
	v_readlane_b32 s73, v255, 13
	v_lshl_add_u64 v[22:23], s[14:15], 0, v[194:195]
	s_addc_u32 s41, s4, s1
	v_or_b32_e32 v33, 0x8000, v3
	v_lshlrev_b32_e32 v34, 1, v7
	v_add_u32_e32 v35, v4, v2
	v_add_u32_e32 v36, v5, v6
	s_mov_b32 s50, s2
	v_readlane_b32 s74, v255, 14
	v_readlane_b32 s75, v255, 15
	v_readlane_b32 s76, v255, 16
	v_readlane_b32 s77, v255, 17
	v_readlane_b32 s78, v255, 18
	v_readlane_b32 s79, v255, 19
	v_readlane_b32 s80, v255, 20
	v_readlane_b32 s81, v255, 21
	v_readlane_b32 s82, v255, 22
	v_readlane_b32 s83, v255, 23
	v_readlane_b32 s84, v255, 24
	v_readlane_b32 s85, v255, 25
	v_readlane_b32 s86, v255, 26
	v_readlane_b32 s87, v255, 27
	s_branch .LBB0_191

; __global__ void __launch_bounds__(512, 2) fwd_megakernel(Args a) {
;     ...
;             if (f < 3) { const MetaEpi me{nullptr, nullptr, 0, f == 0 ? a.meta : nullptr, hb, ssq + (size_t)(np + 1) * M, 0.5f, f == 0 ? 1 : 0};
;                 meta_gemm<2>(lds, act + (size_t)128 * (FF / 64) * 16384, 64, 16384, (const bf16*)(ws + WS_WDN) + (size_t)f * D * FF, FF, D / 32, me, G, c); }
;             pg8::Gemm g{act, (const bf16*)(ws + WS_WDN) + (size_t)f * D * FF, MR, D, FF, 64, 0, 32768u, (size_t)(FF / 64) * 32768}; pg8::StaticOrder S; S.init(MR, D, G, c, REV_DOWN);
;             pg8::EpiResid E{f == 0 ? a.x : nullptr, f == 0 ? a.meta : nullptr, hb, ssq + (size_t)(np + 1) * M, a.out, 0.5f, f == 3 ? 1 : 0};
;             pg8::gemm_phase<pg8::EpiResid, pg8::StaticOrder, true, true>(lds, g, S, E);
.LBB0_204:
	s_cmp_eq_u32 s98, 2
	s_cbranch_scc0 .Ldm_cont
	s_mov_b64 s[0:1], s[100:101]
	s_branch .Ldm_gsync

; #define GSYNC() xcd_barrier(xbar)
; __global__ void __launch_bounds__(512, 2) fwd_megakernel(Args a) {
;     ...
;             pg8::gemm_phase<pg8::EpiResid, pg8::StaticOrder, true, true>(lds, g, S, E);
;         }
;         ++np;
;         if (f == 3) break;
;         GSYNC();
.LBB0_300:
	s_cmp_eq_u32 s98, 1
	s_cbranch_scc0 .Ldm_gsync
	s_mov_b32 s98, 2
	s_mov_b64 s[100:101], s[0:1]
	s_branch .Ldm_meta_entry

; __global__ void __launch_bounds__(512, 2) fwd_megakernel(Args a) {
	.amdhsa_kernel _Z14fwd_megakernel4Args
		.amdhsa_group_segment_fixed_size 0
		.amdhsa_private_segment_fixed_size 0
		.amdhsa_kernarg_size 392
		.amdhsa_user_sgpr_count 2
		.amdhsa_user_sgpr_dispatch_ptr 0
		.amdhsa_user_sgpr_queue_ptr 0
		.amdhsa_user_sgpr_kernarg_segment_ptr 1
		.amdhsa_user_sgpr_dispatch_id 0
		.amdhsa_user_sgpr_kernarg_preload_length 0
		.amdhsa_user_sgpr_kernarg_preload_offset 0
		.amdhsa_user_sgpr_private_segment_size 0
		.amdhsa_uses_dynamic_stack 0
		.amdhsa_enable_private_segment 0
		.amdhsa_system_sgpr_workgroup_id_x 1
		.amdhsa_system_sgpr_workgroup_id_y 0
		.amdhsa_system_sgpr_workgroup_id_z 0
		.amdhsa_system_sgpr_workgroup_info 0
		.amdhsa_system_vgpr_workitem_id 2
		.amdhsa_next_free_vgpr 256
		.amdhsa_next_free_sgpr 102
		.amdhsa_accum_offset 256
		.amdhsa_reserve_vcc 1
		.amdhsa_float_round_mode_32 0
		.amdhsa_float_round_mode_16_64 0
		.amdhsa_float_denorm_mode_32 3
		.amdhsa_float_denorm_mode_16_64 3
		.amdhsa_dx10_clamp 1
		.amdhsa_ieee_mode 1
		.amdhsa_fp16_overflow 0
		.amdhsa_tg_split 0
		.amdhsa_exception_fp_ieee_invalid_op 0
		.amdhsa_exception_fp_denorm_src 0
		.amdhsa_exception_fp_ieee_div_zero 0
		.amdhsa_exception_fp_ieee_overflow 0
		.amdhsa_exception_fp_ieee_underflow 0
		.amdhsa_exception_fp_ieee_inexact 0
		.amdhsa_exception_int_div_zero 0
	.end_amdhsa_kernel

; __global__ void __launch_bounds__(512, 2) fwd_megakernel(Args a) {
amdhsa.kernels:
  - .agpr_count:     0
    .args:
      - .offset:         0
        .size:           136
        .value_kind:     by_value
      - .offset:         136
        .size:           4
        .value_kind:     hidden_block_count_x
      - .offset:         140
        .size:           4
        .value_kind:     hidden_block_count_y
      - .offset:         144
        .size:           4
        .value_kind:     hidden_block_count_z
      - .offset:         148
        .size:           2
        .value_kind:     hidden_group_size_x
      - .offset:         150
        .size:           2
        .value_kind:     hidden_group_size_y
      - .offset:         152
        .size:           2
        .value_kind:     hidden_group_size_z
      - .offset:         154
        .size:           2
        .value_kind:     hidden_remainder_x
      - .offset:         156
        .size:           2
        .value_kind:     hidden_remainder_y
      - .offset:         158
        .size:           2
        .value_kind:     hidden_remainder_z
      - .offset:         176
        .size:           8
        .value_kind:     hidden_global_offset_x
      - .offset:         184
        .size:           8
        .value_kind:     hidden_global_offset_y
      - .offset:         192
        .size:           8
        .value_kind:     hidden_global_offset_z
      - .offset:         200
        .size:           2
        .value_kind:     hidden_grid_dims
      - .offset:         224
        .size:           8
        .value_kind:     hidden_multigrid_sync_arg
      - .offset:         256
        .size:           4
        .value_kind:     hidden_dynamic_lds_size
    .group_segment_fixed_size: 0
    .kernarg_segment_align: 8
    .kernarg_segment_size: 392
    .language:       OpenCL C
    .language_version:
      - 2
      - 0
    .max_flat_workgroup_size: 512
    .name:           _Z14fwd_megakernel4Args
    .private_segment_fixed_size: 0
    .sgpr_count:     108
    .sgpr_spill_count: 161
    .symbol:         _Z14fwd_megakernel4Args.kd
    .uniform_work_group_size: 1
    .uses_dynamic_stack: false
    .vgpr_count:     256
    .vgpr_spill_count: 0
    .wavefront_size: 64
